# skips the pointless grid barrier after the last layer; otherwise same as previous best (no cg grid.sync, faster barrier follower path, P3/P4/P5 scheduling changes, hand-written GDN scan)
# baseline (speedup 1.0000x reference)
.LBB0_1153:
	v_readlane_b32 s2, v255, 30
	s_nop 0
	s_cmp_eq_u32 s2, 3
	s_cbranch_scc1 .LBB0_1204
	s_waitcnt vmcnt(0)
	s_waitcnt lgkmcnt(0)
	s_barrier
	s_mov_b64 s[36:37], exec
	v_readlane_b32 s2, v254, 4
	v_readlane_b32 s3, v254, 5
	s_and_b64 s[2:3], s[36:37], s[2:3]
	s_mov_b64 exec, s[2:3]
	s_cbranch_execnz .LBB0_1154
	s_getpc_b64 s[98:99]
